# on top of v55: per-phase schedule byte fetched with a scalar load (scalar cache) instead of a vector load + vmcnt(0) after the L2 invalidate
# speedup vs baseline: 1.0034x; 1.0034x over previous
.LBB0_13:
	v_mov_b32_e32 v196, v201
	v_readlane_b32 s0, v255, 4
	s_mov_b32 s55, s96
	s_mov_b32 s56, s0
	v_readlane_b32 s34, v255, 6
	v_readfirstlane_b32 s0, v196
	v_readlane_b32 s1, v255, 5
	v_readlane_b32 s35, v255, 7
	v_writelane_b32 v255, s0, 38
	s_mov_b32 s3, s2
	s_ashr_i32 s2, s0, 6
	s_lshl_b32 s0, s55, 3
	s_add_i32 s90, s2, s0
	s_lshl_b32 s92, s56, 3
	s_lshl_b32 s4, s55, 9
	s_lshl_b32 s84, s56, 9
	s_add_u32 s76, s34, 0x22d00000
	s_addc_u32 s77, s35, 0
	s_add_u32 s86, s34, 0x200000
	s_addc_u32 s87, s35, 0
	s_add_u32 s0, s34, 0x900000
	s_addc_u32 s1, s35, 0
	v_writelane_b32 v255, s0, 39
	v_add_u32_e32 v198, s4, v196
	v_and_b32_e32 v200, 63, v196
	v_writelane_b32 v255, s1, 40
	s_add_u32 s0, s34, 0x934000
	s_addc_u32 s1, s35, 0
	v_writelane_b32 v255, s0, 41
	s_nop 1
	v_writelane_b32 v255, s1, 42
	s_add_u32 s0, s34, 0x968000
	s_addc_u32 s1, s35, 0
	s_add_u32 s58, s34, 0x3c00000
	s_addc_u32 s59, s35, 0
	s_add_u32 s78, s34, 0x7c00000
	s_addc_u32 s79, s35, 0
	v_writelane_b32 v255, s0, 43
	s_add_u32 s74, s34, 0x1ec00000
	s_addc_u32 s75, s35, 0
	v_writelane_b32 v255, s1, 44
	s_lshl_b32 s0, s2, 14
	v_writelane_b32 v255, s2, 45
	s_add_i32 s0, s0, 0
	s_ashr_i32 s2, s3, 31
	v_writelane_b32 v255, s0, 46
	s_getpc_b64 s[0:1]
	s_add_u32 s0, s0, SCHED@rel32@lo+4
	s_addc_u32 s1, s1, SCHED@rel32@hi+12
	s_and_b32 s2, s3, -4
	s_load_dword s30, s[0:1], s2
	v_writelane_b32 v255, s3, 47
	v_writelane_b32 v255, s4, 48
	s_and_b32 s2, s3, 3
	s_lshl_b32 s2, s2, 3
	s_waitcnt lgkmcnt(0)
	s_lshr_b32 s0, s30, s2
	s_and_b32 s0, s0, 0xff
	s_and_b32 s1, s0, 0xff
	s_and_b32 s30, s0, 15
	s_bfe_u32 s83, s0, 0x20006
	s_bfe_u32 s72, s1, 0x20004
	s_bfe_u32 s4, s1, 0x10004
	s_cmp_eq_u32 s4, 0
	v_writelane_b32 v255, s1, 49
	s_cselect_b64 s[0:1], -1, 0
	s_and_b64 s[2:3], s[0:1], exec
	s_cselect_b32 s3, s35, s93
	s_cselect_b32 s2, s34, s91
	v_writelane_b32 v255, s2, 50
	s_mul_i32 s4, s4, 0x44000
	s_nop 0
	v_writelane_b32 v255, s3, 51
	s_add_u32 s2, s34, 0xa00000
	s_addc_u32 s3, s35, 0
	s_add_u32 s85, s2, s4
	v_writelane_b32 v255, s2, 52
	s_addc_u32 s88, s3, 0
	v_writelane_b32 v255, s3, 53
	s_cmp_lt_i32 s30, 6
	s_mov_b64 s[4:5], -1
	s_cbranch_scc1 .LBB0_447
	s_and_b64 s[0:1], s[0:1], exec
	s_cselect_b32 s1, s93, s35
	s_cselect_b32 s0, s91, s34
	v_writelane_b32 v255, s0, 54
	s_cmp_lt_i32 s30, 9
	s_nop 0
	v_writelane_b32 v255, s1, 55
	s_mov_b64 s[0:1], -1
	s_cbranch_scc1 .LBB0_105
	s_cmp_lt_i32 s30, 10
	s_cbranch_scc1 .LBB0_29
	s_cmp_lt_i32 s30, 11
	s_cbranch_scc1 .LBB0_23
	s_cmp_eq_u32 s30, 11
	s_cbranch_scc0 .LBB0_22
	v_readlane_b32 s0, v255, 10
	s_nop 1
	v_mov_b32_e32 v1, s0
	ds_read_b64 v[2:3], v1
	s_mov_b32 s0, 0x400000
	v_cmp_gt_i32_e32 vcc, s0, v198
	s_waitcnt lgkmcnt(0)
	v_readfirstlane_b32 s5, v3
	v_readfirstlane_b32 s4, v2
	s_and_saveexec_b64 s[6:7], vcc
	s_cbranch_execz .LBB0_21
	v_lshlrev_b32_e32 v1, 3, v196
	v_lshl_add_u32 v1, s55, 12, v1
	s_lshl_b32 s2, s56, 12
	s_mov_b64 s[8:9], 0
	v_mov_b32_e32 v4, v198
